# v68 plus retention chunk loop: the 8 Q-fragment LDS reads of the output section issued early (after barrier 1) into fresh registers, lgkmcnt waits re-derived
# speedup vs baseline: 1.0089x; 1.0053x over previous
; #define LAS __attribute__((address_space(3)))
; #define LBAR() do { asm volatile("s_waitcnt lgkmcnt(0)" ::: "memory"); __builtin_amdgcn_s_barrier(); asm volatile("" ::: "memory"); } while (0)
; __device__ __forceinline__ void retention_unit(LAS unsigned char* lds, const Ptrs& P, int b, int h, int tid) {
;     ...
;         if (n < 32) {
; #pragma unroll
;             for (int j2 = 0; j2 < 2; ++j2) {
;                 const int jt = (w & 1) * 2 + j2; f32x4 a4 = (f32x4){0.f, 0.f, 0.f, 0.f};
; #pragma unroll
;                 for (int ks = 0; ks < 2; ++ks) {
;                     const bf16x8 qf = *(const LAS bf16x8*)(Qs + (16 * it3 + fr) * S72 + 32 * ks + 8 * fq), kf = *(const LAS bf16x8*)(Ks + (16 * jt + fr) * S72 + 32 * ks + 8 * fq);
;                     a4 = mfma16(kf, qf, a4); }
;                 a4 = a4 * decv[j2];
;                 v2u pw; pw.x = pk2(a4[0], a4[1]); pw.y = pk2(a4[2], a4[3]);
;                 *(LAS v2u*)(Ss + (16 * it3 + fr) * S72 + 16 * jt + 4 * fq) = pw;
;             }
;         }
;         LBAR();
;         if (n >= 1) {
; #pragma unroll
;             for (int it = 0; it < 4; ++it) { const int i = 16 * it + fr; const float mean = stat[i * 2], rstd = stat[i * 2 + 1]; const v2u sg = sgr[it];
;                 const f32x4 y = (op[it] - mean) * rstd * gng4 * (f32x4){bflo(sg.x), bfhi(sg.x), bflo(sg.y), bfhi(sg.y)};
;                 v2u pw; pw.x = pk2(y[0], y[1]); pw.y = pk2(y[2], y[3]);
;                 *(v2u*)(gol + ((size_t)(n - 1) * 64 + 16 * it) * 1024) = pw; }
;         }
;         if (n < 32) {
;             f32x4 o[4]; bf16x8 bst[2], bv[2];
; #pragma unroll
;             for (int ks = 0; ks < 2; ++ks) { bst[ks] = *(const LAS bf16x8*)(St + (16 * w + fr) * S72 + 32 * ks + 8 * fq); bv[ks] = tr_frag(bufc + ROFF_V, S144 * 2, w, ks, fq, fr); }
; #pragma unroll
;             for (int it = 0; it < 4; ++it) { o[it] = (f32x4){0.f, 0.f, 0.f, 0.f};
; #pragma unroll
;                 for (int ks = 0; ks < 2; ++ks) { const bf16x8 qf = *(const LAS bf16x8*)(Qs + (16 * it + fr) * S72 + 32 * ks + 8 * fq); o[it] = mfma16(bst[ks], qf, o[it]); }
;                 o[it] = o[it] * dqv[it];
; #pragma unroll
;                 for (int ks = 0; ks < 2; ++ks) { const bf16x8 sf = *(const LAS bf16x8*)(Ss + (16 * it + fr) * S72 + 32 * ks + 8 * fq); o[it] = mfma16(bv[ks], sf, o[it]); }
;             }
.LBB0_657:
	s_or_b64 exec, exec, s[18:19]
	v_lshl_add_u32 v60, v155, 1, s90
	v_add_u32_e32 v61, v60, v179
	s_waitcnt lgkmcnt(0)
	ds_read_b128 v[56:59], v61 offset:9216
	v_add_u32_e32 v75, v60, v62
	ds_read_b128 v[184:187], v61 offset:9280
	ds_read_b128 v[188:191], v75
	ds_read_b128 v[192:195], v75 offset:64
	v_add_u32_e32 v60, v60, v178
	s_waitcnt vmcnt(7)
	v_and_b32_e32 v61, 0xffff0000, v54
	v_add_u32_e32 v75, 0, v160
	v_add_u32_e32 v143, 0x21400, v75
	v_lshl_add_u64 v[120:121], s[26:27], 0, v[114:115]
	v_add3_u32 v204, s90, v82, v169
	s_waitcnt lgkmcnt(1)
	v_mfma_f32_16x16x32_bf16 v[56:59], v[56:59], v[188:191], 0
	s_add_i32 s18, s90, s87
	s_waitcnt vmcnt(5)
	v_lshlrev_b32_e32 v200, 16, v122
	v_and_b32_e32 v201, 0xffff0000, v122
	s_waitcnt lgkmcnt(0)
	v_mfma_f32_16x16x32_bf16 v[56:59], v[184:187], v[192:195], v[56:59]
	v_lshlrev_b32_e32 v122, 16, v123
	v_and_b32_e32 v123, 0xffff0000, v123
	v_add3_u32 v212, s90, v162, v170
	v_mov_b32_e32 v75, v74
	v_pk_mul_f32 v[18:19], v[74:75], v[18:19]
	s_nop 2
	v_pk_mul_f32 v[58:59], v[100:101], v[58:59]
	v_pk_mul_f32 v[56:57], v[98:99], v[56:57]
	v_pk_mul_f32 v[16:17], v[76:77], v[16:17]
	v_cvt_pk_bf16_f32 v56, v56, v57
	v_cvt_pk_bf16_f32 v57, v58, v59
	ds_write_b64 v177, v[56:57]
	ds_read_b128 v[56:59], v60 offset:9216
	ds_read_b128 v[184:187], v60 offset:9280
	ds_read_b128 v[216:219], v204
	ds_read_b128 v[220:223], v204 offset:64
	ds_read_b128 v[224:227], v204 offset:2304
	ds_read_b128 v[228:231], v204 offset:2368
	ds_read_b128 v[232:235], v204 offset:4608
	ds_read_b128 v[236:239], v204 offset:4672
	ds_read_b128 v[240:243], v204 offset:6912
	ds_read_b128 v[244:247], v204 offset:6976
	s_waitcnt lgkmcnt(9)
	v_mfma_f32_16x16x32_bf16 v[56:59], v[56:59], v[188:191], 0
	v_lshlrev_b32_e32 v60, 16, v54
	v_lshlrev_b32_e32 v188, 16, v55
	v_and_b32_e32 v189, 0xffff0000, v55
	s_waitcnt lgkmcnt(8)
	v_mfma_f32_16x16x32_bf16 v[54:57], v[184:187], v[192:195], v[56:59]
	v_mul_f32_e64 v14, v74, v14
	v_mul_f32_e64 v15, v75, v15
	v_pk_mul_f32 v[12:13], v[76:77], v[12:13]
	v_pk_mul_f32 v[10:11], v[74:75], v[10:11]
	v_add_co_u32_e32 v58, vcc, s66, v120
	v_pk_mul_f32 v[8:9], v[76:77], v[8:9]
	s_nop 1
	v_pk_mul_f32 v[56:57], v[94:95], v[56:57]
	v_pk_mul_f32 v[54:55], v[92:93], v[54:55]
	v_addc_co_u32_e32 v59, vcc, 0, v121, vcc
	v_cvt_pk_bf16_f32 v54, v54, v55
	v_cvt_pk_bf16_f32 v55, v56, v57
	ds_write_b64 v142, v[54:55]
	s_waitcnt lgkmcnt(0)
	s_barrier
	ds_read2_b64 v[54:57], v143 offset1:16
	ds_read_b128 v[184:187], v137
	v_pk_mul_f32 v[6:7], v[74:75], v[6:7]
	v_pk_mul_f32 v[4:5], v[76:77], v[4:5]
	v_lshl_add_u64 v[110:111], v[110:111], 0, s[8:9]
	s_waitcnt lgkmcnt(1)
	v_sub_f32_e32 v41, v41, v54
	v_sub_f32_e32 v40, v40, v54
	v_sub_f32_e32 v43, v43, v54
	v_sub_f32_e32 v42, v42, v54
	v_pk_mul_f32 v[42:43], v[54:55], v[42:43] op_sel:[1,0]
	v_pk_mul_f32 v[40:41], v[54:55], v[40:41] op_sel:[1,0]
	v_pk_mul_f32 v[42:43], v[2:3], v[42:43]
	v_pk_mul_f32 v[40:41], v[0:1], v[40:41]
	v_pk_mul_f32 v[42:43], v[42:43], v[188:189]
	v_pk_mul_f32 v[40:41], v[40:41], v[60:61]
	v_sub_f32_e32 v45, v45, v56
	v_cvt_pk_bf16_f32 v40, v40, v41
	v_cvt_pk_bf16_f32 v41, v42, v43
	v_sub_f32_e32 v44, v44, v56
	global_store_dwordx2 v[58:59], v[40:41], off
	v_sub_f32_e32 v41, v47, v56
	v_sub_f32_e32 v40, v46, v56
	v_pk_mul_f32 v[40:41], v[56:57], v[40:41] op_sel:[1,0]
	v_pk_mul_f32 v[42:43], v[56:57], v[44:45] op_sel:[1,0]
	ds_read2_b64 v[54:57], v143 offset0:32 offset1:48
	v_pk_mul_f32 v[42:43], v[0:1], v[42:43]
	v_pk_mul_f32 v[40:41], v[2:3], v[40:41]
	v_lshlrev_b32_e32 v44, 16, v52
	v_and_b32_e32 v45, 0xffff0000, v52
	v_lshlrev_b32_e32 v46, 16, v53
	v_and_b32_e32 v47, 0xffff0000, v53
	v_pk_mul_f32 v[40:41], v[40:41], v[46:47]
	v_pk_mul_f32 v[42:43], v[42:43], v[44:45]
	ds_read_b128 v[188:191], v137 offset:64
	v_cvt_pk_bf16_f32 v42, v42, v43
	v_cvt_pk_bf16_f32 v43, v40, v41
	v_add_co_u32_e32 v40, vcc, s67, v120
	s_nop 0
	v_addc_co_u32_e32 v41, vcc, 0, v121, vcc
	global_store_dwordx2 v[40:41], v[42:43], off
	s_waitcnt lgkmcnt(1)
	v_sub_f32_e32 v41, v49, v54
	v_sub_f32_e32 v40, v48, v54
	v_sub_f32_e32 v43, v51, v54
	v_sub_f32_e32 v42, v50, v54
	v_pk_mul_f32 v[40:41], v[54:55], v[40:41] op_sel:[1,0]
	v_pk_mul_f32 v[192:193], v[54:55], v[42:43] op_sel:[1,0]
	v_pk_mul_f32 v[196:197], v[0:1], v[40:41]
	s_waitcnt lgkmcnt(0)
	v_mfma_f32_16x16x32_bf16 v[40:43], v[184:187], v[216:219], 0
	v_add3_u32 v48, s18, v162, v168
	ds_read_b64_tr_b16 v[58:59], v48 offset:27648
	ds_read_b64_tr_b16 v[60:61], v48 offset:28800
	ds_read_b64_tr_b16 v[52:53], v48 offset:36864
	ds_read_b64_tr_b16 v[54:55], v48 offset:38016
	ds_read_b128 v[48:51], v129
	v_pk_mul_f32 v[192:193], v[2:3], v[192:193]
	v_mfma_f32_16x16x32_bf16 v[40:43], v[188:191], v[220:223], v[40:43]
	ds_read_b128 v[44:47], v129 offset:64
	v_pk_mul_f32 v[122:123], v[192:193], v[122:123]
	ds_read_b128 v[192:195], v129 offset:2304
	v_lshl_add_u64 v[112:113], v[112:113], 0, s[12:13]
	v_lshl_add_u64 v[114:115], v[114:115], 0, s[14:15]
	s_nop 2
	v_pk_mul_f32 v[42:43], v[108:109], v[42:43]
	v_pk_mul_f32 v[40:41], v[90:91], v[40:41]
	s_cmp_lg_u32 s89, 30
	v_lshl_add_u64 v[116:117], v[116:117], 0, s[12:13]
	s_waitcnt lgkmcnt(2)
	v_mfma_f32_16x16x32_bf16 v[40:43], v[58:61], v[48:51], v[40:43]
	s_waitcnt lgkmcnt(1)
	v_mfma_f32_16x16x32_bf16 v[40:43], v[52:55], v[44:47], v[40:43]
	s_waitcnt lgkmcnt(0)
	v_mfma_f32_16x16x32_bf16 v[48:51], v[184:187], v[224:227], 0
	s_waitcnt lgkmcnt(0)
	v_mfma_f32_16x16x32_bf16 v[44:47], v[188:191], v[228:231], v[48:51]
	s_nop 5
	ds_read_b128 v[48:51], v129 offset:2368
	s_nop 0
	v_pk_mul_f32 v[46:47], v[106:107], v[46:47]
	v_pk_mul_f32 v[44:45], v[78:79], v[44:45]
	s_nop 1
	v_mfma_f32_16x16x32_bf16 v[44:47], v[58:61], v[192:195], v[44:47]
	v_mul_f32_e64 v192, v196, v200
	v_mul_f32_e64 v193, v197, v201
	ds_read_b128 v[200:203], v129 offset:4608
	v_cvt_pk_bf16_f32 v192, v192, v193
	s_waitcnt lgkmcnt(1)
; #define LAS __attribute__((address_space(3)))
; __device__ __forceinline__ unsigned pk2(float lo, float hi) { return pg8::cvt_pk_bf16(lo, hi); }
; __device__ __forceinline__ f32x4 mfma16(bf16x8 a, bf16x8 b, f32x4 c) { return __builtin_amdgcn_mfma_f32_16x16x32_bf16(a, b, c, 0, 0, 0); }
; __device__ __forceinline__ void retention_unit(LAS unsigned char* lds, const Ptrs& P, int b, int h, int tid) {
;     ...
;         if (n < 32) {
;             f32x4 o[4]; bf16x8 bst[2], bv[2];
; #pragma unroll
;             for (int ks = 0; ks < 2; ++ks) { bst[ks] = *(const LAS bf16x8*)(St + (16 * w + fr) * S72 + 32 * ks + 8 * fq); bv[ks] = tr_frag(bufc + ROFF_V, S144 * 2, w, ks, fq, fr); }
; #pragma unroll
;             for (int it = 0; it < 4; ++it) { o[it] = (f32x4){0.f, 0.f, 0.f, 0.f};
; #pragma unroll
;                 for (int ks = 0; ks < 2; ++ks) { const bf16x8 qf = *(const LAS bf16x8*)(Qs + (16 * it + fr) * S72 + 32 * ks + 8 * fq); o[it] = mfma16(bst[ks], qf, o[it]); }
;                 o[it] = o[it] * dqv[it];
; #pragma unroll
;                 for (int ks = 0; ks < 2; ++ks) { const bf16x8 sf = *(const LAS bf16x8*)(Ss + (16 * it + fr) * S72 + 32 * ks + 8 * fq); o[it] = mfma16(bv[ks], sf, o[it]); }
;             }
; #pragma unroll
;             for (int dt = 0; dt < 4; ++dt) { st[dt] = st[dt] * dch;
; #pragma unroll
;                 for (int ks = 0; ks < 2; ++ks) { const bf16x8 kf = tr_frag(bufc + ROFF_K2, S72 * 2, dt, ks, fq, fr); st[dt] = mfma16(kf, bv[ks], st[dt]); }
;                 v2u pw; pw.x = pk2(st[dt][0], st[dt][1]); pw.y = pk2(st[dt][2], st[dt][3]);
;                 *(LAS v2u*)(St + (16 * w + fr) * S72 + 16 * dt + 4 * fq) = pw; }
; #pragma unroll
;             for (int it = 0; it < 4; ++it) { const f32x4 v = o[it]; typedef float f32x2 __attribute__((ext_vector_type(2)));
;                 *(LAS f32x2*)(part + ((16 * it + fr) * 32 + w * 4 + fq) * 2) = (f32x2){(v[0] + v[1]) + (v[2] + v[3]), (v[0] * v[0] + v[1] * v[1]) + (v[2] * v[2] + v[3] * v[3])};
;                 op[it] = v; }
	v_mfma_f32_16x16x32_bf16 v[44:47], v[52:55], v[48:51], v[44:47]
	v_cvt_pk_bf16_f32 v193, v122, v123
	v_add_co_u32_e32 v122, vcc, s68, v120
	v_sub_f32_e32 v197, v23, v56
	s_nop 0
	v_addc_co_u32_e32 v123, vcc, 0, v121, vcc
	global_store_dwordx2 v[122:123], v[192:193], off
	s_waitcnt lgkmcnt(0)
	v_mfma_f32_16x16x32_bf16 v[48:51], v[184:187], v[232:235], 0
	v_sub_f32_e32 v123, v21, v56
	v_sub_f32_e32 v122, v20, v56
	v_sub_f32_e32 v196, v22, v56
	s_waitcnt lgkmcnt(0)
	v_mfma_f32_16x16x32_bf16 v[48:51], v[188:191], v[236:239], v[48:51]
	ds_read_b128 v[192:195], v129 offset:4672
	v_pk_mul_f32 v[196:197], v[56:57], v[196:197] op_sel:[1,0]
	v_pk_mul_f32 v[56:57], v[56:57], v[122:123] op_sel:[1,0]
	v_pk_mul_f32 v[122:123], v[2:3], v[196:197]
	v_pk_mul_f32 v[56:57], v[0:1], v[56:57]
	s_nop 2
	v_pk_mul_f32 v[50:51], v[104:105], v[50:51]
	v_pk_mul_f32 v[48:49], v[86:87], v[48:49]
	s_waitcnt vmcnt(7)
	v_lshlrev_b32_e32 v196, 16, v118
	v_and_b32_e32 v197, 0xffff0000, v118
	v_mfma_f32_16x16x32_bf16 v[48:51], v[58:61], v[200:203], v[48:51]
	ds_read_b64_tr_b16 v[200:201], v212 offset:18432
	ds_read_b64_tr_b16 v[202:203], v212 offset:19008
	ds_read_b64_tr_b16 v[20:21], v212 offset:23040
	ds_read_b64_tr_b16 v[22:23], v212 offset:23616
	s_waitcnt lgkmcnt(2)
	v_mfma_f32_16x16x32_bf16 v[16:19], v[200:203], v[58:61], v[16:19]
	s_waitcnt lgkmcnt(0)
	v_mfma_f32_16x16x32_bf16 v[16:19], v[20:23], v[52:55], v[16:19]
	v_mfma_f32_16x16x32_bf16 v[48:51], v[52:55], v[192:195], v[48:51]
	ds_read_b128 v[204:207], v129 offset:6912
	ds_read_b128 v[208:211], v129 offset:6976
	s_nop 2
	v_cvt_pk_bf16_f32 v20, v16, v17
	v_cvt_pk_bf16_f32 v21, v18, v19
	ds_write_b64 v132, v[20:21]
	ds_read_b64_tr_b16 v[20:21], v212 offset:18464
	ds_read_b64_tr_b16 v[22:23], v212 offset:19040
	s_waitcnt lgkmcnt(5)
	v_mfma_f32_16x16x32_bf16 v[184:187], v[184:187], v[240:243], 0
	ds_read_b64_tr_b16 v[192:193], v212 offset:23072
	ds_read_b64_tr_b16 v[194:195], v212 offset:23648
	s_waitcnt lgkmcnt(2)
	v_mfma_f32_16x16x32_bf16 v[12:15], v[20:23], v[58:61], v[12:15]
	s_waitcnt lgkmcnt(0)
	v_mfma_f32_16x16x32_bf16 v[12:15], v[192:195], v[52:55], v[12:15]
	v_mfma_f32_16x16x32_bf16 v[184:187], v[188:191], v[244:247], v[184:187]
	s_nop 6
	v_cvt_pk_bf16_f32 v20, v12, v13
	v_cvt_pk_bf16_f32 v21, v14, v15
	ds_write_b64 v132, v[20:21] offset:32
	ds_read_b64_tr_b16 v[20:21], v212 offset:18496
	ds_read_b64_tr_b16 v[22:23], v212 offset:19072
	ds_read_b64_tr_b16 v[188:189], v212 offset:23104
	ds_read_b64_tr_b16 v[190:191], v212 offset:23680
	s_waitcnt lgkmcnt(2)
	v_mfma_f32_16x16x32_bf16 v[8:11], v[20:23], v[58:61], v[8:11]
	v_mul_f32_e64 v186, v96, v186
	v_mul_f32_e64 v187, v97, v187
	v_pk_mul_f32 v[184:185], v[88:89], v[184:185]
	v_lshlrev_b32_e32 v20, 16, v119
	s_waitcnt lgkmcnt(0)
	v_mfma_f32_16x16x32_bf16 v[8:11], v[188:191], v[52:55], v[8:11]
	v_and_b32_e32 v21, 0xffff0000, v119
	v_pk_mul_f32 v[20:21], v[122:123], v[20:21]
	v_mfma_f32_16x16x32_bf16 v[184:187], v[58:61], v[204:207], v[184:187]
	s_nop 4
	v_cvt_pk_bf16_f32 v22, v8, v9
	v_cvt_pk_bf16_f32 v23, v10, v11
	ds_write_b64 v132, v[22:23] offset:64
	ds_read_b64_tr_b16 v[188:189], v212 offset:18528
	ds_read_b64_tr_b16 v[190:191], v212 offset:19104
	v_pk_mul_f32 v[22:23], v[56:57], v[196:197]
	v_cvt_pk_bf16_f32 v57, v20, v21
	v_cvt_pk_bf16_f32 v56, v22, v23
	v_mfma_f32_16x16x32_bf16 v[20:23], v[52:55], v[208:211], v[184:187]
	s_nop 2
	ds_read_b64_tr_b16 v[184:185], v212 offset:23136
	ds_read_b64_tr_b16 v[186:187], v212 offset:23712
	s_waitcnt lgkmcnt(2)
	v_mfma_f32_16x16x32_bf16 v[4:7], v[188:191], v[58:61], v[4:7]
	v_add_co_u32_e32 v58, vcc, s69, v120
	s_waitcnt lgkmcnt(0)
	v_mfma_f32_16x16x32_bf16 v[4:7], v[184:187], v[52:55], v[4:7]
	v_addc_co_u32_e32 v59, vcc, 0, v121, vcc
	global_store_dwordx2 v[58:59], v[56:57], off
	v_mul_f32_e32 v55, v41, v41
	v_mul_f32_e32 v57, v42, v42
	s_nop 3
	v_cvt_pk_bf16_f32 v52, v4, v5
	v_cvt_pk_bf16_f32 v53, v6, v7
	ds_write_b64 v132, v[52:53] offset:96
	v_mul_f32_e32 v53, v40, v40
	v_mul_f32_e32 v59, v43, v43
	v_mov_b32_e32 v52, v40
	v_mov_b32_e32 v54, v41
	v_mov_b32_e32 v56, v42
	v_mov_b32_e32 v58, v43
	v_pk_add_f32 v[52:53], v[52:53], v[54:55]
	v_pk_add_f32 v[54:55], v[56:57], v[58:59]
	v_mul_f32_e32 v57, v46, v46
	v_pk_add_f32 v[52:53], v[52:53], v[54:55]
	ds_write_b64 v133, v[52:53]
	v_mul_f32_e32 v53, v44, v44
	v_mul_f32_e32 v55, v45, v45
	v_mul_f32_e32 v59, v47, v47
	v_mov_b32_e32 v52, v44
	v_mov_b32_e32 v54, v45
	v_mov_b32_e32 v56, v46
	v_mov_b32_e32 v58, v47
	v_pk_add_f32 v[52:53], v[52:53], v[54:55]
	v_pk_add_f32 v[54:55], v[56:57], v[58:59]
	v_mul_f32_e32 v57, v50, v50
	v_pk_add_f32 v[52:53], v[52:53], v[54:55]
	ds_write_b64 v134, v[52:53]
	v_mul_f32_e32 v53, v48, v48
	v_mul_f32_e32 v55, v49, v49
	v_mul_f32_e32 v59, v51, v51
	v_mov_b32_e32 v52, v48
	v_mov_b32_e32 v54, v49
	v_mov_b32_e32 v56, v50
	v_mov_b32_e32 v58, v51
	v_pk_add_f32 v[52:53], v[52:53], v[54:55]
	v_pk_add_f32 v[54:55], v[56:57], v[58:59]
	v_mul_f32_e32 v57, v22, v22
	v_pk_add_f32 v[52:53], v[52:53], v[54:55]
	ds_write_b64 v135, v[52:53]
	v_mul_f32_e32 v53, v20, v20
	v_mul_f32_e32 v55, v21, v21
	v_mul_f32_e32 v59, v23, v23
	v_mov_b32_e32 v52, v20
	v_mov_b32_e32 v54, v21
	v_mov_b32_e32 v56, v22
	v_mov_b32_e32 v58, v23
	v_pk_add_f32 v[52:53], v[52:53], v[54:55]
	v_pk_add_f32 v[54:55], v[56:57], v[58:59]
	s_nop 0
	v_pk_add_f32 v[52:53], v[52:53], v[54:55]
	ds_write_b64 v136, v[52:53]
	s_cbranch_scc0 .LBB0_660
